# H3 step 5: plain v_rsq_f32 instead of the denormal-scaled rsqrt sequence (argument ss/128+eps is never denormal; bit-identical), -64 VALU per wave per item; on top of v065
# speedup vs baseline: 1.0058x; 1.0023x over previous
; __device__ __forceinline__ float sigmoidf_(float x) { return __builtin_amdgcn_rcpf(1.f + __expf(-x)); }
; __device__ __forceinline__ unsigned short bf1(float x) { unsigned r; asm("v_cvt_pk_bf16_f32 %0, %1, %1" : "=v"(r) : "v"(x)); return (unsigned short)r; }
; __device__ __forceinline__ void h3_phase(const Ptrs& P, LAS unsigned char* lds, int bx, int G, int tid) {
;     ...
;         __syncthreads();
;         const int e = 16 * w + fr;
; #pragma unroll
;         for (int m = 0; m < 4; ++m)
; #pragma unroll
;             for (int jj = 0; jj < 4; ++jj) { const int t = 16 * m + 4 * fq + jj; const float ss = red[t];
;                 const float rs = rsqrtf(ss * (1.f / HD) + EPS);
;                 const float gv = (float)GST[t * 128 + e];
;                 const float yv = o[m][jj] * rs * nwv * gv * sigmoidf_(gv);
;     ...
;                 YST[t * 128 + e] = bf1(yv);
;     ...
;                 YST[t * 128 + e] = __builtin_bit_cast(unsigned short, (h16)yv);
;     ...
;             }
.LBB0_352:
	s_or_b64 exec, exec, s[58:59]
	s_waitcnt lgkmcnt(0)
	s_barrier
	ds_read_b32 v176, v121
	ds_read_u16 v177, v122
	ds_read_b32 v178, v124
	ds_read_u16 v179, v125
	ds_read_b32 v180, v127
	ds_read_u16 v181, v128
	ds_read_b32 v182, v130
	ds_read_b32 v183, v96
	s_waitcnt lgkmcnt(7)
	v_fmamk_f32 v176, v176, 0x3c000000, v175
	s_waitcnt lgkmcnt(6)
	v_cvt_f32_f16_e32 v177, v177
	s_lshl_b32 s58, s75, 2
	s_andn2_b32 s58, s58, 63
	v_rsq_f32_e32 v176, v176
	v_mul_f32_e32 v184, 0xbfb8aa3b, v177
	v_exp_f32_e32 v184, v184
	s_ashr_i32 s59, s58, 31
	v_mul_f32_e32 v48, v48, v176
	s_waitcnt lgkmcnt(5)
	v_fmamk_f32 v176, v178, 0x3c000000, v175
	s_waitcnt lgkmcnt(4)
	v_cvt_f32_f16_e32 v178, v179
	v_add_f32_e32 v184, 1.0, v184
	v_mul_f32_e32 v48, v77, v48
	v_rcp_f32_e32 v184, v184
	v_mul_f32_e32 v48, v48, v177
	v_mul_f32_e32 v48, v184, v48
	v_cvt_pk_bf16_f32 v48, v48, v48
	ds_write_b16 v123, v48
	v_rsq_f32_e32 v176, v176
	v_mul_f32_e32 v177, 0xbfb8aa3b, v178
	v_exp_f32_e32 v177, v177
	s_lshl_b64 s[58:59], s[58:59], 12
	v_mov_b32_e32 v48, v176
	v_add_f32_e32 v176, 1.0, v177
	v_rcp_f32_e32 v176, v176
	v_mul_f32_e32 v48, v49, v48
	v_mul_f32_e32 v48, v77, v48
	s_waitcnt lgkmcnt(3)
	v_cvt_f32_f16_e32 v177, v181
	v_mul_f32_e32 v48, v48, v178
	v_fmamk_f32 v49, v180, 0x3c000000, v175
	v_mul_f32_e32 v48, v176, v48
	v_cvt_pk_bf16_f32 v48, v48, v48
	ds_write_b16 v126, v48
	s_lshl_b32 s60, s74, 7
	v_rsq_f32_e32 v49, v49
	v_mul_f32_e32 v176, 0xbfb8aa3b, v177
	v_exp_f32_e32 v176, v176
	s_or_b32 s58, s58, s60
	v_mov_b32_e32 v48, v49
	v_add_f32_e32 v49, 1.0, v176
	v_rcp_f32_e32 v49, v49
	v_mul_f32_e32 v48, v50, v48
	v_mul_f32_e32 v48, v77, v48
	v_mul_f32_e32 v48, v48, v177
	v_mul_f32_e32 v48, v49, v48
	s_waitcnt lgkmcnt(3)
	v_fmamk_f32 v49, v182, 0x3c000000, v175
	ds_read_u16 v176, v131
	ds_read_b32 v177, v133
	ds_read_u16 v178, v134
	ds_read_b32 v179, v136
	ds_read_u16 v180, v137
	ds_read_b32 v181, v139
	ds_read_u16 v182, v140
	ds_read_b32 v184, v142
	s_waitcnt lgkmcnt(7)
	v_cvt_f32_f16_e32 v176, v176
	v_cvt_pk_bf16_f32 v48, v48, v48
	ds_write_b16 v129, v48
	s_mov_b64 s[60:61], -1
	v_rsq_f32_e32 v49, v49
	v_mul_f32_e32 v50, 0xbfb8aa3b, v176
	v_exp_f32_e32 v50, v50
	s_mov_b32 s75, s62
	v_mov_b32_e32 v48, v49
	v_add_f32_e32 v49, 1.0, v50
	v_rcp_f32_e32 v49, v49
	v_mul_f32_e32 v48, v51, v48
	v_mul_f32_e32 v48, v77, v48
	v_mul_f32_e32 v48, v48, v176
	s_waitcnt lgkmcnt(6)
	v_cvt_f32_f16_e32 v51, v178
	v_mul_f32_e32 v48, v49, v48
	v_fmamk_f32 v49, v177, 0x3c000000, v175
	v_cvt_pk_bf16_f32 v48, v48, v48
	ds_write_b16 v132, v48
	s_nop 0
	v_rsq_f32_e32 v49, v49
	v_mul_f32_e32 v50, 0xbfb8aa3b, v51
	v_exp_f32_e32 v50, v50
	v_mov_b32_e32 v48, v49
	v_add_f32_e32 v49, 1.0, v50
	v_rcp_f32_e32 v49, v49
	v_mul_f32_e32 v44, v44, v48
	v_mul_f32_e32 v44, v77, v44
	s_waitcnt lgkmcnt(5)
	v_cvt_f32_f16_e32 v50, v180
	v_mul_f32_e32 v44, v44, v51
	v_fmamk_f32 v48, v179, 0x3c000000, v175
	v_mul_f32_e32 v44, v49, v44
	v_cvt_pk_bf16_f32 v44, v44, v44
	ds_write_b16 v135, v44
	s_nop 0
	v_rsq_f32_e32 v48, v48
	v_mul_f32_e32 v49, 0xbfb8aa3b, v50
	v_exp_f32_e32 v49, v49
	v_mov_b32_e32 v44, v48
	v_add_f32_e32 v48, 1.0, v49
	v_rcp_f32_e32 v48, v48
	v_mul_f32_e32 v44, v45, v44
	v_mul_f32_e32 v44, v77, v44
	s_waitcnt lgkmcnt(4)
	v_cvt_f32_f16_e32 v49, v182
	v_mul_f32_e32 v44, v44, v50
	v_fmamk_f32 v45, v181, 0x3c000000, v175
	v_mul_f32_e32 v44, v48, v44
	v_cvt_pk_bf16_f32 v44, v44, v44
	ds_write_b16 v138, v44
	s_nop 0
	v_rsq_f32_e32 v45, v45
	v_mul_f32_e32 v48, 0xbfb8aa3b, v49
	v_exp_f32_e32 v48, v48
	v_mov_b32_e32 v44, v45
	v_add_f32_e32 v45, 1.0, v48
	v_rcp_f32_e32 v45, v45
	v_mul_f32_e32 v44, v46, v44
	v_mul_f32_e32 v44, v77, v44
	v_mul_f32_e32 v44, v44, v49
	ds_read_u16 v48, v143
	ds_read_b32 v49, v145
	ds_read_u16 v50, v146
	ds_read_b32 v51, v148
	ds_read_u16 v176, v149
	ds_read_b32 v177, v151
	ds_read_u16 v178, v152
	ds_read_b32 v179, v154
	s_waitcnt lgkmcnt(7)
	v_cvt_f32_f16_e32 v48, v48
	v_mul_f32_e32 v44, v45, v44
	v_fmamk_f32 v45, v184, 0x3c000000, v175
	v_cvt_pk_bf16_f32 v44, v44, v44
	ds_write_b16 v141, v44
	s_nop 0
	v_rsq_f32_e32 v45, v45
	v_mul_f32_e32 v46, 0xbfb8aa3b, v48
	v_exp_f32_e32 v46, v46
	v_mov_b32_e32 v44, v45
	v_add_f32_e32 v45, 1.0, v46
	v_rcp_f32_e32 v45, v45
	v_mul_f32_e32 v44, v47, v44
	v_mul_f32_e32 v44, v77, v44
	v_mul_f32_e32 v44, v44, v48
	s_waitcnt lgkmcnt(6)
; __device__ __forceinline__ float sigmoidf_(float x) { return __builtin_amdgcn_rcpf(1.f + __expf(-x)); }
; __device__ __forceinline__ unsigned short bf1(float x) { unsigned r; asm("v_cvt_pk_bf16_f32 %0, %1, %1" : "=v"(r) : "v"(x)); return (unsigned short)r; }
; __device__ __forceinline__ void h3_phase(const Ptrs& P, LAS unsigned char* lds, int bx, int G, int tid) {
;     ...
; #pragma unroll
;         for (int m = 0; m < 4; ++m)
; #pragma unroll
;             for (int jj = 0; jj < 4; ++jj) { const int t = 16 * m + 4 * fq + jj; const float ss = red[t];
;                 const float rs = rsqrtf(ss * (1.f / HD) + EPS);
;                 const float gv = (float)GST[t * 128 + e];
;                 const float yv = o[m][jj] * rs * nwv * gv * sigmoidf_(gv);
;     ...
;                 YST[t * 128 + e] = bf1(yv);
;     ...
;                 YST[t * 128 + e] = __builtin_bit_cast(unsigned short, (h16)yv);
;     ...
;             }
;         yoff = (size_t)t0 * D + h * HD; have_y = true;
;     }
	v_cvt_f32_f16_e32 v47, v50
	v_mul_f32_e32 v44, v45, v44
	v_fmamk_f32 v45, v49, 0x3c000000, v175
	v_cvt_pk_bf16_f32 v44, v44, v44
	ds_write_b16 v144, v44
	s_nop 0
	v_rsq_f32_e32 v45, v45
	v_mul_f32_e32 v46, 0xbfb8aa3b, v47
	v_exp_f32_e32 v46, v46
	v_mov_b32_e32 v44, v45
	v_add_f32_e32 v45, 1.0, v46
	v_rcp_f32_e32 v45, v45
	v_mul_f32_e32 v40, v40, v44
	v_mul_f32_e32 v40, v77, v40
	s_waitcnt lgkmcnt(5)
	v_cvt_f32_f16_e32 v46, v176
	v_mul_f32_e32 v40, v40, v47
	v_fmamk_f32 v44, v51, 0x3c000000, v175
	v_mul_f32_e32 v40, v45, v40
	v_cvt_pk_bf16_f32 v40, v40, v40
	ds_write_b16 v147, v40
	s_nop 0
	v_rsq_f32_e32 v44, v44
	v_mul_f32_e32 v45, 0xbfb8aa3b, v46
	v_exp_f32_e32 v45, v45
	v_mov_b32_e32 v40, v44
	v_add_f32_e32 v44, 1.0, v45
	v_rcp_f32_e32 v44, v44
	v_mul_f32_e32 v40, v41, v40
	v_mul_f32_e32 v40, v77, v40
	s_waitcnt lgkmcnt(4)
	v_cvt_f32_f16_e32 v45, v178
	v_mul_f32_e32 v40, v40, v46
	v_fmamk_f32 v41, v177, 0x3c000000, v175
	v_mul_f32_e32 v40, v44, v40
	v_cvt_pk_bf16_f32 v40, v40, v40
	ds_write_b16 v150, v40
	s_nop 0
	v_rsq_f32_e32 v41, v41
	v_mul_f32_e32 v44, 0xbfb8aa3b, v45
	v_exp_f32_e32 v44, v44
	v_mov_b32_e32 v40, v41
	v_add_f32_e32 v41, 1.0, v44
	v_rcp_f32_e32 v41, v41
	v_mul_f32_e32 v40, v42, v40
	v_mul_f32_e32 v40, v77, v40
	v_mul_f32_e32 v40, v40, v45
	ds_read_u16 v44, v155
	ds_read_u16 v45, v157
	ds_read_b32 v46, v159
	ds_read_u16 v47, v160
	ds_read_b32 v48, v162
	ds_read_u16 v49, v163
	ds_read_b32 v50, v165
	ds_read_u16 v51, v166
	s_waitcnt lgkmcnt(7)
	v_cvt_f32_f16_e32 v44, v44
	v_mul_f32_e32 v40, v41, v40
	v_fmamk_f32 v41, v179, 0x3c000000, v175
	v_cvt_pk_bf16_f32 v40, v40, v40
	ds_write_b16 v153, v40
	s_nop 0
	v_rsq_f32_e32 v41, v41
	v_mul_f32_e32 v42, 0xbfb8aa3b, v44
	v_exp_f32_e32 v42, v42
	v_mov_b32_e32 v40, v41
	v_add_f32_e32 v41, 1.0, v42
	v_rcp_f32_e32 v41, v41
	v_mul_f32_e32 v40, v43, v40
	v_mul_f32_e32 v40, v77, v40
	v_mul_f32_e32 v40, v40, v44
	s_waitcnt lgkmcnt(7)
	v_cvt_f32_f16_e32 v43, v45
	v_mul_f32_e32 v40, v41, v40
	v_fmamk_f32 v41, v183, 0x3c000000, v175
	v_cvt_pk_bf16_f32 v40, v40, v40
	ds_write_b16 v156, v40
	s_nop 0
	v_rsq_f32_e32 v41, v41
	v_mul_f32_e32 v42, 0xbfb8aa3b, v43
	v_exp_f32_e32 v42, v42
	v_mov_b32_e32 v40, v41
	v_add_f32_e32 v41, 1.0, v42
	v_rcp_f32_e32 v41, v41
	v_mul_f32_e32 v36, v36, v40
	v_mul_f32_e32 v36, v77, v36
	s_waitcnt lgkmcnt(6)
	v_cvt_f32_f16_e32 v42, v47
	v_mul_f32_e32 v36, v36, v43
	v_fmamk_f32 v40, v46, 0x3c000000, v175
	v_mul_f32_e32 v36, v41, v36
	v_cvt_pk_bf16_f32 v36, v36, v36
	ds_write_b16 v158, v36
	s_waitcnt vmcnt(2)
	v_mov_b64_e32 v[44:45], v[56:57]
	v_rsq_f32_e32 v40, v40
	v_mul_f32_e32 v41, 0xbfb8aa3b, v42
	v_exp_f32_e32 v41, v41
	v_mov_b64_e32 v[46:47], v[58:59]
	v_mov_b32_e32 v36, v40
	v_add_f32_e32 v40, 1.0, v41
	v_rcp_f32_e32 v40, v40
	v_mul_f32_e32 v36, v37, v36
	v_mul_f32_e32 v36, v77, v36
	s_waitcnt lgkmcnt(5)
	v_cvt_f32_f16_e32 v41, v49
	v_mul_f32_e32 v36, v36, v42
	v_fmamk_f32 v37, v48, 0x3c000000, v175
	v_mul_f32_e32 v36, v40, v36
	v_cvt_pk_bf16_f32 v36, v36, v36
	ds_write_b16 v161, v36
	s_nop 0
	v_rsq_f32_e32 v37, v37
	v_mul_f32_e32 v40, 0xbfb8aa3b, v41
	v_exp_f32_e32 v40, v40
	v_mov_b32_e32 v36, v37
	v_add_f32_e32 v37, 1.0, v40
	v_rcp_f32_e32 v37, v37
	v_mul_f32_e32 v36, v38, v36
	v_mul_f32_e32 v36, v77, v36
	v_mul_f32_e32 v36, v36, v41
	s_waitcnt lgkmcnt(4)
	v_cvt_f32_f16_e32 v40, v51
	v_mul_f32_e32 v36, v37, v36
	v_fmamk_f32 v37, v50, 0x3c000000, v175
	v_cvt_pk_bf16_f32 v36, v36, v36
	ds_write_b16 v164, v36
	v_mov_b64_e32 v[48:49], v[52:53]
	v_rsq_f32_e32 v37, v37
	v_mul_f32_e32 v38, 0xbfb8aa3b, v40
	v_exp_f32_e32 v38, v38
	v_mov_b64_e32 v[50:51], v[54:55]
	v_mov_b32_e32 v36, v37
	v_add_f32_e32 v37, 1.0, v38
	v_rcp_f32_e32 v37, v37
	v_mul_f32_e32 v36, v39, v36
	v_mul_f32_e32 v36, v77, v36
	v_mul_f32_e32 v36, v36, v40
	v_mul_f32_e32 v36, v37, v36
	v_cvt_pk_bf16_f32 v36, v36, v36
	ds_write_b16 v167, v36
	s_waitcnt vmcnt(1)
	v_mov_b64_e32 v[40:41], v[60:61]
	s_waitcnt vmcnt(0)
	v_mov_b64_e32 v[36:37], v[64:65]
	s_and_b64 vcc, exec, s[56:57]
	v_mov_b64_e32 v[42:43], v[62:63]
	v_mov_b64_e32 v[38:39], v[66:67]
	s_cbranch_vccnz .LBB0_404
